# v119 variant: global-loop DMA issue after QK MFMA 0 (K) and 2 (V) instead of 1 and 5
# baseline (speedup 1.0000x reference)
.Lgo_vs:
.Lgo_nv:
	s_add_i32 s72, s7, 2
	s_mul_hi_u32 s80, s72, 0x55555556
	s_mul_i32 s80, s80, 3
	s_sub_u32 s80, s72, s80
	s_lshl_b32 s81, s80, 13
	s_cmp_eq_u32 s80, 2
	s_cselect_b32 s81, 0x6000, s81
	v_add_u32_e32 v242, s81, v253
	s_add_i32 s72, s7, 1
	s_and_b32 s80, s72, 3
	s_lshl_b32 s81, s80, 13
	s_cmp_eq_u32 s80, 3
	s_cselect_b32 s81, 0xe000, s81
	v_add_u32_e32 v243, s81, v221
	ds_read_b64_tr_b16 v[160:161], v242 offset:24576
	ds_read_b64_tr_b16 v[162:163], v242 offset:25088
	ds_read_b64_tr_b16 v[164:165], v242 offset:25600
	ds_read_b64_tr_b16 v[166:167], v242 offset:26112
	ds_read_b64_tr_b16 v[168:169], v242 offset:26624
	ds_read_b64_tr_b16 v[170:171], v242 offset:27136
	ds_read_b64_tr_b16 v[172:173], v242 offset:27648
	ds_read_b64_tr_b16 v[174:175], v242 offset:28160
	v_mfma_f32_32x32x16_bf16 v[80:95], v[128:131], v[96:99], 0
	v_add_f32_e32 v204, v204, v32
	v_add_f32_e32 v205, v205, v33
	v_add_f32_e32 v208, v208, v34
	v_add_f32_e32 v209, v209, v35
	v_cvt_pk_bf16_f32 v112, v32, v33
	v_cvt_pk_bf16_f32 v113, v34, v35
	s_and_b64 vcc, exec, s[82:83]
	s_cbranch_vccz .Lgo_mk
	s_add_i32 s96, s7, 3
	s_and_b32 s80, s96, 3
	s_lshl_b32 s81, s80, 13
	s_cmp_eq_u32 s80, 3
	s_cselect_b32 s81, 0xe000, s81
	s_add_i32 s81, s81, s100
	s_mov_b32 m0, s81
	s_nop 0
	global_load_lds_dwordx4 v[244:245], off
	v_lshl_add_u64 v[244:245], v[244:245], 0, s[98:99]
.Lgo_mk:
	v_mfma_f32_32x32x16_bf16 v[48:63], v[132:135], v[96:99], 0
	v_add_f32_e32 v204, v204, v36
	v_add_f32_e32 v205, v205, v37
	v_add_f32_e32 v208, v208, v38
	v_add_f32_e32 v209, v209, v39
	v_cvt_pk_bf16_f32 v114, v36, v37
	v_cvt_pk_bf16_f32 v115, v38, v39
	v_mfma_f32_32x32x16_bf16 v[80:95], v[136:139], v[100:103], v[80:95]
	v_add_f32_e32 v204, v204, v40
	v_add_f32_e32 v205, v205, v41
	v_add_f32_e32 v208, v208, v42
	v_add_f32_e32 v209, v209, v43
	v_cvt_pk_bf16_f32 v116, v40, v41
	v_cvt_pk_bf16_f32 v117, v42, v43
	s_add_i32 s96, s7, 1
	s_cmp_lt_i32 s96, s71
	s_cbranch_scc0 .Lgo_mv
	s_mul_hi_u32 s80, s96, 0x55555556
	s_mul_i32 s80, s80, 3
	s_sub_u32 s80, s96, s80
	s_lshl_b32 s81, s80, 13
	s_cmp_eq_u32 s80, 2
	s_cselect_b32 s81, 0x6000, s81
	s_add_i32 s81, s81, 0x6000
	s_add_i32 s81, s81, s100
	s_mov_b32 m0, s81
	s_nop 0
	global_load_lds_dwordx4 v[246:247], off
	v_lshl_add_u64 v[246:247], v[246:247], 0, s[98:99]
.Lgo_mv:
	v_mfma_f32_32x32x16_bf16 v[48:63], v[140:143], v[100:103], v[48:63]
	v_add_f32_e32 v204, v204, v44
	v_add_f32_e32 v205, v205, v45
	v_add_f32_e32 v208, v208, v46
	v_add_f32_e32 v209, v209, v47
	v_cvt_pk_bf16_f32 v118, v44, v45
	v_cvt_pk_bf16_f32 v119, v46, v47
	v_mfma_f32_32x32x16_bf16 v[80:95], v[144:147], v[104:107], v[80:95]
	v_add_f32_e32 v204, v204, v64
	v_add_f32_e32 v205, v205, v65
	v_add_f32_e32 v208, v208, v66
	v_add_f32_e32 v209, v209, v67
	v_cvt_pk_bf16_f32 v120, v64, v65
	v_cvt_pk_bf16_f32 v121, v66, v67
	v_mfma_f32_32x32x16_bf16 v[48:63], v[148:151], v[104:107], v[48:63]
	v_add_f32_e32 v204, v204, v68
	v_add_f32_e32 v205, v205, v69
	v_add_f32_e32 v208, v208, v70
	v_add_f32_e32 v209, v209, v71
	v_cvt_pk_bf16_f32 v122, v68, v69
	v_cvt_pk_bf16_f32 v123, v70, v71
	v_mfma_f32_32x32x16_bf16 v[80:95], v[152:155], v[108:111], v[80:95]
	v_add_f32_e32 v204, v204, v72
	v_add_f32_e32 v205, v205, v73
	v_add_f32_e32 v208, v208, v74
	v_add_f32_e32 v209, v209, v75
	v_cvt_pk_bf16_f32 v124, v72, v73
	v_cvt_pk_bf16_f32 v125, v74, v75
	v_mfma_f32_32x32x16_bf16 v[48:63], v[156:159], v[108:111], v[48:63]
	v_add_f32_e32 v204, v204, v76
	v_add_f32_e32 v205, v205, v77
	v_add_f32_e32 v208, v208, v78
	v_add_f32_e32 v209, v209, v79
	v_cvt_pk_bf16_f32 v126, v76, v77
	v_cvt_pk_bf16_f32 v127, v78, v79
	ds_read_b64_tr_b16 v[176:177], v242 offset:28672
	ds_read_b64_tr_b16 v[178:179], v242 offset:29184
	ds_read_b64_tr_b16 v[180:181], v242 offset:29696
	ds_read_b64_tr_b16 v[182:183], v242 offset:30208
	ds_read_b64_tr_b16 v[184:185], v242 offset:30720
	ds_read_b64_tr_b16 v[186:187], v242 offset:31232
	ds_read_b64_tr_b16 v[188:189], v242 offset:31744
	s_waitcnt lgkmcnt(14)
	ds_read_b64_tr_b16 v[190:191], v242 offset:32256
	s_waitcnt lgkmcnt(14)
	v_mfma_f32_32x32x16_bf16 v[0:15], v[160:163], v[112:115], v[0:15]
	v_exp_f32_e32 v80, v80
	v_exp_f32_e32 v81, v81
	v_exp_f32_e32 v82, v82
	v_exp_f32_e32 v83, v83
	s_waitcnt lgkmcnt(12)
	v_mfma_f32_32x32x16_bf16 v[0:15], v[164:167], v[116:119], v[0:15]
	v_exp_f32_e32 v84, v84
	v_exp_f32_e32 v85, v85
	v_exp_f32_e32 v86, v86
	v_exp_f32_e32 v87, v87
	s_waitcnt lgkmcnt(10)
	v_mfma_f32_32x32x16_bf16 v[0:15], v[168:171], v[120:123], v[0:15]
	v_exp_f32_e32 v88, v88
	v_exp_f32_e32 v89, v89
	v_exp_f32_e32 v90, v90
	v_exp_f32_e32 v91, v91
	ds_read_b128 v[128:131], v243
	ds_read_b128 v[132:135], v243 offset:512
	s_waitcnt lgkmcnt(10)
	v_mfma_f32_32x32x16_bf16 v[0:15], v[172:175], v[124:127], v[0:15]
	v_exp_f32_e32 v92, v92
	v_exp_f32_e32 v93, v93
	v_exp_f32_e32 v94, v94
	v_exp_f32_e32 v95, v95
	ds_read_b128 v[136:139], v243 offset:2048
	ds_read_b128 v[140:143], v243 offset:2560
	s_waitcnt lgkmcnt(10)
	v_mfma_f32_32x32x16_bf16 v[16:31], v[176:179], v[112:115], v[16:31]
	v_exp_f32_e32 v48, v48
	v_exp_f32_e32 v49, v49
	v_exp_f32_e32 v50, v50
	v_exp_f32_e32 v51, v51
	ds_read_b128 v[144:147], v243 offset:4096
	ds_read_b128 v[148:151], v243 offset:4608
	s_waitcnt lgkmcnt(10)
	v_mfma_f32_32x32x16_bf16 v[16:31], v[180:183], v[116:119], v[16:31]
	v_exp_f32_e32 v52, v52
	v_exp_f32_e32 v53, v53
	v_exp_f32_e32 v54, v54
	v_exp_f32_e32 v55, v55
	ds_read_b128 v[152:155], v243 offset:6144
	ds_read_b128 v[156:159], v243 offset:6656
	s_waitcnt lgkmcnt(10)
	v_mfma_f32_32x32x16_bf16 v[16:31], v[184:187], v[120:123], v[16:31]
	v_exp_f32_e32 v56, v56
	v_exp_f32_e32 v57, v57
	v_exp_f32_e32 v58, v58
	v_exp_f32_e32 v59, v59
	s_waitcnt lgkmcnt(8)
	v_mfma_f32_32x32x16_bf16 v[16:31], v[188:191], v[124:127], v[16:31]
	v_exp_f32_e32 v60, v60
	v_exp_f32_e32 v61, v61
	v_exp_f32_e32 v62, v62
	v_exp_f32_e32 v63, v63
	s_waitcnt lgkmcnt(0)
	s_and_b64 vcc, exec, s[82:83]
	s_cbranch_vccz .Lgo_w0
	s_waitcnt vmcnt(2)
	s_branch .Lgo_w1

.Lge_vs:
.Lge_nv:
	s_add_i32 s72, s7, 2
	s_mul_hi_u32 s80, s72, 0x55555556
	s_mul_i32 s80, s80, 3
	s_sub_u32 s80, s72, s80
	s_lshl_b32 s81, s80, 13
	s_cmp_eq_u32 s80, 2
	s_cselect_b32 s81, 0x6000, s81
	v_add_u32_e32 v242, s81, v253
	s_add_i32 s72, s7, 1
	s_and_b32 s80, s72, 3
	s_lshl_b32 s81, s80, 13
	s_cmp_eq_u32 s80, 3
	s_cselect_b32 s81, 0xe000, s81
	v_add_u32_e32 v243, s81, v221
	ds_read_b64_tr_b16 v[160:161], v242 offset:24576
	ds_read_b64_tr_b16 v[162:163], v242 offset:25088
	ds_read_b64_tr_b16 v[164:165], v242 offset:25600
	ds_read_b64_tr_b16 v[166:167], v242 offset:26112
	ds_read_b64_tr_b16 v[168:169], v242 offset:26624
	ds_read_b64_tr_b16 v[170:171], v242 offset:27136
	ds_read_b64_tr_b16 v[172:173], v242 offset:27648
	ds_read_b64_tr_b16 v[174:175], v242 offset:28160
	v_mfma_f32_32x32x16_bf16 v[32:47], v[128:131], v[96:99], 0
	v_add_f32_e32 v204, v204, v80
	v_add_f32_e32 v205, v205, v81
	v_add_f32_e32 v208, v208, v82
	v_add_f32_e32 v209, v209, v83
	v_cvt_pk_bf16_f32 v112, v80, v81
	v_cvt_pk_bf16_f32 v113, v82, v83
	s_and_b64 vcc, exec, s[82:83]
	s_cbranch_vccz .Lge_mk
	s_add_i32 s96, s7, 3
	s_and_b32 s80, s96, 3
	s_lshl_b32 s81, s80, 13
	s_cmp_eq_u32 s80, 3
	s_cselect_b32 s81, 0xe000, s81
	s_add_i32 s81, s81, s100
	s_mov_b32 m0, s81
	s_nop 0
	global_load_lds_dwordx4 v[244:245], off
	v_lshl_add_u64 v[244:245], v[244:245], 0, s[98:99]
.Lge_mk:
	v_mfma_f32_32x32x16_bf16 v[64:79], v[132:135], v[96:99], 0
	v_add_f32_e32 v204, v204, v84
	v_add_f32_e32 v205, v205, v85
	v_add_f32_e32 v208, v208, v86
	v_add_f32_e32 v209, v209, v87
	v_cvt_pk_bf16_f32 v114, v84, v85
	v_cvt_pk_bf16_f32 v115, v86, v87
	v_mfma_f32_32x32x16_bf16 v[32:47], v[136:139], v[100:103], v[32:47]
	v_add_f32_e32 v204, v204, v88
	v_add_f32_e32 v205, v205, v89
	v_add_f32_e32 v208, v208, v90
	v_add_f32_e32 v209, v209, v91
	v_cvt_pk_bf16_f32 v116, v88, v89
	v_cvt_pk_bf16_f32 v117, v90, v91
	s_add_i32 s96, s7, 1
	s_cmp_lt_i32 s96, s71
	s_cbranch_scc0 .Lge_mv
	s_mul_hi_u32 s80, s96, 0x55555556
	s_mul_i32 s80, s80, 3
	s_sub_u32 s80, s96, s80
	s_lshl_b32 s81, s80, 13
	s_cmp_eq_u32 s80, 2
	s_cselect_b32 s81, 0x6000, s81
	s_add_i32 s81, s81, 0x6000
	s_add_i32 s81, s81, s100
	s_mov_b32 m0, s81
	s_nop 0
	global_load_lds_dwordx4 v[246:247], off
	v_lshl_add_u64 v[246:247], v[246:247], 0, s[98:99]
.Lge_mv:
	v_mfma_f32_32x32x16_bf16 v[64:79], v[140:143], v[100:103], v[64:79]
	v_add_f32_e32 v204, v204, v92
	v_add_f32_e32 v205, v205, v93
	v_add_f32_e32 v208, v208, v94
	v_add_f32_e32 v209, v209, v95
	v_cvt_pk_bf16_f32 v118, v92, v93
	v_cvt_pk_bf16_f32 v119, v94, v95
	v_mfma_f32_32x32x16_bf16 v[32:47], v[144:147], v[104:107], v[32:47]
	v_add_f32_e32 v204, v204, v48
	v_add_f32_e32 v205, v205, v49
	v_add_f32_e32 v208, v208, v50
	v_add_f32_e32 v209, v209, v51
	v_cvt_pk_bf16_f32 v120, v48, v49
	v_cvt_pk_bf16_f32 v121, v50, v51
	v_mfma_f32_32x32x16_bf16 v[64:79], v[148:151], v[104:107], v[64:79]
	v_add_f32_e32 v204, v204, v52
	v_add_f32_e32 v205, v205, v53
	v_add_f32_e32 v208, v208, v54
	v_add_f32_e32 v209, v209, v55
	v_cvt_pk_bf16_f32 v122, v52, v53
	v_cvt_pk_bf16_f32 v123, v54, v55
	v_mfma_f32_32x32x16_bf16 v[32:47], v[152:155], v[108:111], v[32:47]
	v_add_f32_e32 v204, v204, v56
	v_add_f32_e32 v205, v205, v57
	v_add_f32_e32 v208, v208, v58
	v_add_f32_e32 v209, v209, v59
	v_cvt_pk_bf16_f32 v124, v56, v57
	v_cvt_pk_bf16_f32 v125, v58, v59
	v_mfma_f32_32x32x16_bf16 v[64:79], v[156:159], v[108:111], v[64:79]
	v_add_f32_e32 v204, v204, v60
	v_add_f32_e32 v205, v205, v61
	v_add_f32_e32 v208, v208, v62
	v_add_f32_e32 v209, v209, v63
	v_cvt_pk_bf16_f32 v126, v60, v61
	v_cvt_pk_bf16_f32 v127, v62, v63
	ds_read_b64_tr_b16 v[176:177], v242 offset:28672
	ds_read_b64_tr_b16 v[178:179], v242 offset:29184
	ds_read_b64_tr_b16 v[180:181], v242 offset:29696
	ds_read_b64_tr_b16 v[182:183], v242 offset:30208
	ds_read_b64_tr_b16 v[184:185], v242 offset:30720
	ds_read_b64_tr_b16 v[186:187], v242 offset:31232
	ds_read_b64_tr_b16 v[188:189], v242 offset:31744
	s_waitcnt lgkmcnt(14)
	ds_read_b64_tr_b16 v[190:191], v242 offset:32256
	s_waitcnt lgkmcnt(14)
	v_mfma_f32_32x32x16_bf16 v[0:15], v[160:163], v[112:115], v[0:15]
	v_exp_f32_e32 v32, v32
	v_exp_f32_e32 v33, v33
	v_exp_f32_e32 v34, v34
	v_exp_f32_e32 v35, v35
	s_waitcnt lgkmcnt(12)
	v_mfma_f32_32x32x16_bf16 v[0:15], v[164:167], v[116:119], v[0:15]
	v_exp_f32_e32 v36, v36
	v_exp_f32_e32 v37, v37
	v_exp_f32_e32 v38, v38
	v_exp_f32_e32 v39, v39
	s_waitcnt lgkmcnt(10)
	v_mfma_f32_32x32x16_bf16 v[0:15], v[168:171], v[120:123], v[0:15]
	v_exp_f32_e32 v40, v40
	v_exp_f32_e32 v41, v41
	v_exp_f32_e32 v42, v42
	v_exp_f32_e32 v43, v43
	ds_read_b128 v[128:131], v243
	ds_read_b128 v[132:135], v243 offset:512
	s_waitcnt lgkmcnt(10)
	v_mfma_f32_32x32x16_bf16 v[0:15], v[172:175], v[124:127], v[0:15]
	v_exp_f32_e32 v44, v44
	v_exp_f32_e32 v45, v45
	v_exp_f32_e32 v46, v46
	v_exp_f32_e32 v47, v47
	ds_read_b128 v[136:139], v243 offset:2048
	ds_read_b128 v[140:143], v243 offset:2560
	s_waitcnt lgkmcnt(10)
	v_mfma_f32_32x32x16_bf16 v[16:31], v[176:179], v[112:115], v[16:31]
	v_exp_f32_e32 v64, v64
	v_exp_f32_e32 v65, v65
	v_exp_f32_e32 v66, v66
	v_exp_f32_e32 v67, v67
	ds_read_b128 v[144:147], v243 offset:4096
	ds_read_b128 v[148:151], v243 offset:4608
	s_waitcnt lgkmcnt(10)
	v_mfma_f32_32x32x16_bf16 v[16:31], v[180:183], v[116:119], v[16:31]
	v_exp_f32_e32 v68, v68
	v_exp_f32_e32 v69, v69
	v_exp_f32_e32 v70, v70
	v_exp_f32_e32 v71, v71
	ds_read_b128 v[152:155], v243 offset:6144
	ds_read_b128 v[156:159], v243 offset:6656
	s_waitcnt lgkmcnt(10)
	v_mfma_f32_32x32x16_bf16 v[16:31], v[184:187], v[120:123], v[16:31]
	v_exp_f32_e32 v72, v72
	v_exp_f32_e32 v73, v73
	v_exp_f32_e32 v74, v74
	v_exp_f32_e32 v75, v75
	s_waitcnt lgkmcnt(8)
	v_mfma_f32_32x32x16_bf16 v[16:31], v[188:191], v[124:127], v[16:31]
	v_exp_f32_e32 v76, v76
	v_exp_f32_e32 v77, v77
	v_exp_f32_e32 v78, v78
	v_exp_f32_e32 v79, v79
	s_waitcnt lgkmcnt(0)
	s_and_b64 vcc, exec, s[82:83]
	s_cbranch_vccz .Lge_w0
	s_waitcnt vmcnt(2)
	s_branch .Lge_w1
